# sample-MLA unit prologue: the 16 latent-query fragment loads and the rope-query loads issued together with counted vmcnt waits (was load, vmcnt(0), LDS write sixteen times in a row)
# baseline (speedup 1.0000x reference)
.LBB0_934:
	s_lshl_b32 s6, s31, 2
	s_and_b32 s6, s6, 28
	s_ashr_i32 s38, s31, 6
	s_add_i32 s10, s6, s38
	s_ashr_i32 s11, s10, 31
	s_bfe_u32 s36, s31, 0x30003
	s_lshl_b64 s[6:7], s[10:11], 6
	s_add_u32 s8, s6, 0x4000
	s_addc_u32 s9, s7, 0
	s_lshl_b64 s[6:7], s[10:11], 18
	s_add_u32 s12, s92, s6
	s_addc_u32 s13, s93, s7
	s_lshl_b32 s37, s36, 9
	s_add_u32 s42, s12, s37
	s_addc_u32 s43, s13, 0
	s_mul_i32 s12, s9, 0x600
	s_mul_hi_u32 s13, s8, 0x600
	s_add_i32 s13, s13, s12
	s_mul_i32 s12, s8, 0x600
	s_add_u32 s12, s76, s12
	s_addc_u32 s13, s77, s13
	s_mul_i32 s37, s36, 0xc0
	s_add_u32 s12, s12, s37
	s_addc_u32 s13, s13, 0
	s_lshl_b64 s[10:11], s[10:11], 21
	v_mov_b32_e32 v4, v0
	s_add_u32 s10, s94, s10
	s_addc_u32 s11, s95, s11
	v_readfirstlane_b32 s37, v4
	s_ashr_i32 s41, s37, 6
	s_and_b32 s46, s41, 1
	s_mul_i32 s39, s46, 0x4800
	v_and_b32_e32 v221, 63, v4
	s_add_i32 s39, s39, 0
	v_and_b32_e32 v220, 31, v4
	s_add_i32 s39, s39, 0x12800
	v_lshlrev_b32_e32 v1, 4, v221
	v_add_u32_e32 v223, s39, v1
	v_lshl_or_b32 v1, s46, 5, v220
	v_bfe_u32 v5, v4, 5, 1
	v_lshlrev_b32_e32 v198, 12, v1
	v_lshl_add_u64 v[2:3], s[42:43], 0, v[198:199]
	v_lshlrev_b32_e32 v198, 4, v5
	v_lshl_add_u64 v[2:3], v[2:3], 0, v[198:199]
	global_load_dwordx4 v[34:37], v[2:3], off
	global_load_dwordx4 v[38:41], v[2:3], off offset:32
	global_load_dwordx4 v[42:45], v[2:3], off offset:64
	global_load_dwordx4 v[46:49], v[2:3], off offset:96
	global_load_dwordx4 v[50:53], v[2:3], off offset:128
	global_load_dwordx4 v[54:57], v[2:3], off offset:160
	global_load_dwordx4 v[58:61], v[2:3], off offset:192
	global_load_dwordx4 v[62:65], v[2:3], off offset:224
	global_load_dwordx4 v[66:69], v[2:3], off offset:256
	global_load_dwordx4 v[70:73], v[2:3], off offset:288
	global_load_dwordx4 v[74:77], v[2:3], off offset:320
	global_load_dwordx4 v[78:81], v[2:3], off offset:352
	global_load_dwordx4 v[82:85], v[2:3], off offset:384
	global_load_dwordx4 v[86:89], v[2:3], off offset:416
	global_load_dwordx4 v[90:93], v[2:3], off offset:448
	global_load_dwordx4 v[94:97], v[2:3], off offset:480
	v_lshlrev_b32_e32 v204, 4, v220
	v_mov_b32_e32 v205, v199
	v_ashrrev_i32_e32 v200, 2, v4
	v_ashrrev_i32_e32 v201, 31, v200
	v_mov_b64_e32 v[2:3], s[12:13]
	v_mad_u64_u32 v[2:3], s[12:13], v1, s33, v[2:3]
	v_lshl_add_u64 v[2:3], v[2:3], 0, v[198:199]
	global_load_dwordx4 v[6:9], v[2:3], off offset:128
	global_load_dwordx4 v[10:13], v[2:3], off offset:160
	s_waitcnt vmcnt(17)
	ds_write_b128 v223, v[34:37]
	s_waitcnt vmcnt(16)
	ds_write_b128 v223, v[38:41] offset:1024
	s_waitcnt vmcnt(15)
	ds_write_b128 v223, v[42:45] offset:2048
	s_waitcnt vmcnt(14)
	ds_write_b128 v223, v[46:49] offset:3072
	s_waitcnt vmcnt(13)
	ds_write_b128 v223, v[50:53] offset:4096
	s_waitcnt vmcnt(12)
	ds_write_b128 v223, v[54:57] offset:5120
	s_waitcnt vmcnt(11)
	ds_write_b128 v223, v[58:61] offset:6144
	s_waitcnt vmcnt(10)
	ds_write_b128 v223, v[62:65] offset:7168
	s_waitcnt vmcnt(9)
	ds_write_b128 v223, v[66:69] offset:8192
	s_waitcnt vmcnt(8)
	ds_write_b128 v223, v[70:73] offset:9216
	s_waitcnt vmcnt(7)
	ds_write_b128 v223, v[74:77] offset:10240
	s_waitcnt vmcnt(6)
	ds_write_b128 v223, v[78:81] offset:11264
	s_waitcnt vmcnt(5)
	ds_write_b128 v223, v[82:85] offset:12288
	s_waitcnt vmcnt(4)
	ds_write_b128 v223, v[86:89] offset:13312
	s_waitcnt vmcnt(3)
	ds_write_b128 v223, v[90:93] offset:14336
	s_waitcnt vmcnt(2)
	ds_write_b128 v223, v[94:97] offset:15360
	v_lshlrev_b32_e32 v2, 6, v5
	v_lshl_or_b32 v2, v1, 7, v2
	v_mov_b32_e32 v3, v199
	v_lshl_add_u64 v[2:3], s[18:19], 0, v[2:3]
	v_lshl_add_u64 v[26:27], v[2:3], 0, s[22:23]
	v_add_co_u32_e32 v2, vcc, s68, v2
	s_waitcnt vmcnt(0)
	v_lshlrev_b32_e32 v30, 16, v10
	v_addc_co_u32_e32 v3, vcc, 0, v3, vcc
	global_load_dwordx4 v[14:17], v[2:3], off
	global_load_dwordx4 v[18:21], v[26:27], off offset:48
	global_load_dwordx4 v[22:25], v[26:27], off offset:32
	s_nop 0
	global_load_dwordx4 v[26:29], v[26:27], off offset:16
	v_and_b32_e32 v31, 0xffff0000, v10
	v_lshlrev_b32_e32 v2, 16, v6
	v_and_b32_e32 v3, 0xffff0000, v6
	s_waitcnt vmcnt(3)
	v_mov_b32_e32 v33, v16
	v_mov_b32_e32 v16, v15
	v_mov_b32_e32 v32, v14
	v_pk_mul_f32 v[14:15], v[16:17], v[30:31]
	s_nop 0
	v_pk_fma_f32 v[14:15], v[32:33], v[2:3], v[14:15] neg_lo:[0,0,1] neg_hi:[0,0,1]
	s_nop 0
	v_cvt_pk_bf16_f32 v6, v14, v15
	v_pk_mul_f32 v[14:15], v[32:33], v[30:31]
	s_nop 0
	v_pk_fma_f32 v[2:3], v[16:17], v[2:3], v[14:15]
	v_lshlrev_b32_e32 v14, 16, v11
	v_and_b32_e32 v15, 0xffff0000, v11
	s_waitcnt vmcnt(0)
	v_mov_b32_e32 v16, v26
	v_mov_b32_e32 v17, v28
	v_mov_b32_e32 v28, v27
	v_cvt_pk_bf16_f32 v10, v2, v3
	v_lshlrev_b32_e32 v2, 16, v7
	v_and_b32_e32 v3, 0xffff0000, v7
	v_pk_mul_f32 v[26:27], v[28:29], v[14:15]
	v_pk_mul_f32 v[14:15], v[16:17], v[14:15]
	v_pk_fma_f32 v[26:27], v[16:17], v[2:3], v[26:27] neg_lo:[0,0,1] neg_hi:[0,0,1]
	v_pk_fma_f32 v[2:3], v[28:29], v[2:3], v[14:15]
	v_lshlrev_b32_e32 v14, 16, v12
	v_and_b32_e32 v15, 0xffff0000, v12
	v_mov_b32_e32 v16, v22
	v_mov_b32_e32 v17, v24
	v_mov_b32_e32 v24, v23
	v_cvt_pk_bf16_f32 v11, v2, v3
	v_lshlrev_b32_e32 v2, 16, v8
	v_and_b32_e32 v3, 0xffff0000, v8
	v_pk_mul_f32 v[22:23], v[24:25], v[14:15]
	v_pk_mul_f32 v[14:15], v[16:17], v[14:15]
	v_pk_fma_f32 v[22:23], v[16:17], v[2:3], v[22:23] neg_lo:[0,0,1] neg_hi:[0,0,1]
	v_pk_fma_f32 v[2:3], v[24:25], v[2:3], v[14:15]
	v_lshlrev_b32_e32 v14, 16, v13
	v_and_b32_e32 v15, 0xffff0000, v13
	v_mov_b32_e32 v16, v18
	v_mov_b32_e32 v17, v20
	v_mov_b32_e32 v20, v19
	v_cvt_pk_bf16_f32 v12, v2, v3
	v_lshlrev_b32_e32 v2, 16, v9
	v_and_b32_e32 v3, 0xffff0000, v9
	v_pk_mul_f32 v[18:19], v[20:21], v[14:15]
	v_pk_mul_f32 v[14:15], v[16:17], v[14:15]
	v_pk_fma_f32 v[18:19], v[16:17], v[2:3], v[18:19] neg_lo:[0,0,1] neg_hi:[0,0,1]
	v_pk_fma_f32 v[2:3], v[20:21], v[2:3], v[14:15]
	v_cvt_pk_bf16_f32 v7, v26, v27
	v_cvt_pk_bf16_f32 v13, v2, v3
	v_ashrrev_i32_e32 v2, 5, v4
	v_ashrrev_i32_e32 v3, 31, v2
	v_cvt_pk_bf16_f32 v8, v22, v23
	v_cvt_pk_bf16_f32 v9, v18, v19
	v_lshlrev_b64 v[202:203], 9, v[2:3]
	ds_write_b128 v223, v[6:9] offset:16384
	ds_write_b128 v223, v[10:13] offset:17408
	v_lshl_add_u64 v[6:7], s[10:11], 0, v[202:203]
	v_lshl_add_u64 v[6:7], v[6:7], 0, v[204:205]
	v_add_co_u32_e32 v8, vcc, s69, v6
	global_load_dwordx4 v[166:169], v[6:7], off
	s_nop 0
	v_addc_co_u32_e32 v9, vcc, 0, v7, vcc
	global_load_dwordx4 v[170:173], v[8:9], off
	v_add_co_u32_e32 v8, vcc, s0, v6
	s_movk_i32 s10, 0x6000
	s_nop 0
	v_addc_co_u32_e32 v9, vcc, 0, v7, vcc
	global_load_dwordx4 v[174:177], v[8:9], off
	v_add_co_u32_e32 v8, vcc, s10, v6
	s_mov_b32 s10, 0x8000
	s_nop 0
	v_addc_co_u32_e32 v9, vcc, 0, v7, vcc
	global_load_dwordx4 v[178:181], v[8:9], off
	v_add_co_u32_e32 v8, vcc, s10, v6
	s_movk_i32 s10, 0x103f
	s_nop 0
	v_addc_co_u32_e32 v9, vcc, 0, v7, vcc
	global_load_dwordx4 v[182:185], v[8:9], off
	v_add_co_u32_e32 v8, vcc, 0xa000, v6
	s_nop 1
	v_addc_co_u32_e32 v9, vcc, 0, v7, vcc
	global_load_dwordx4 v[186:189], v[8:9], off
	v_add_co_u32_e32 v8, vcc, 0xc000, v6
	s_nop 1
	v_addc_co_u32_e32 v9, vcc, 0, v7, vcc
	v_add_co_u32_e32 v6, vcc, 0xe000, v6
	global_load_dwordx4 v[190:193], v[8:9], off
	s_nop 0
	v_addc_co_u32_e32 v7, vcc, 0, v7, vcc
	global_load_dwordx4 v[194:197], v[6:7], off
	v_cmp_lt_i32_e32 vcc, s10, v200
	s_and_saveexec_b64 s[10:11], vcc
	s_xor_b64 s[10:11], exec, s[10:11]
	v_lshlrev_b64 v[206:207], 6, v[200:201]
	s_or_saveexec_b64 s[10:11], s[10:11]
	v_and_b32_e32 v3, 3, v4
	v_lshlrev_b32_e32 v6, 3, v3
	v_lshlrev_b32_e32 v208, 1, v6
	s_xor_b64 exec, exec, s[10:11]
	s_cbranch_execz .LBB0_938
	s_add_u32 s6, s54, s6
	v_readlane_b32 s12, v244, 3
	s_addc_u32 s7, s12, s7
	v_lshlrev_b64 v[206:207], 6, v[200:201]
	v_lshl_add_u64 v[6:7], s[6:7], 0, v[206:207]
	v_mov_b32_e32 v209, v199
	v_lshl_add_u64 v[6:7], v[6:7], 0, v[208:209]
	global_load_dwordx4 v[162:165], v[6:7], off
